# attention epilogue: 64 two-byte global stores per lane replaced by LDS-staged transposition and 8 full-line 16-byte stores (on top of k-inner Gray MFMA order)
# baseline (speedup 1.0000x reference)
.LBB0_442:
	s_or_b64 exec, exec, s[2:3]
	s_waitcnt lgkmcnt(0)
	v_add_u32_e32 v74, v151, v202
	ds_read_b128 v[66:69], v74
	ds_read_b128 v[70:73], v74 offset:32
	s_lshl_b64 s[2:3], s[8:9], 12
	s_add_u32 s2, s64, s2
	s_addc_u32 s3, s65, s3
	s_waitcnt lgkmcnt(1)
	v_rcp_f32_e32 v75, v66
	v_rcp_f32_e32 v76, v67
	v_rcp_f32_e32 v77, v68
	v_rcp_f32_e32 v78, v69
	ds_read_b128 v[66:69], v74 offset:64
	s_lshl_b32 s4, s12, 1
	s_add_u32 s2, s2, s4
	v_ashrrev_i32_e32 v151, 31, v150
	s_addc_u32 s3, s3, 0
	s_waitcnt lgkmcnt(1)
	v_rcp_f32_e32 v79, v70
	v_rcp_f32_e32 v80, v71
	v_rcp_f32_e32 v81, v72
	v_rcp_f32_e32 v82, v73
	ds_read_b128 v[70:73], v74 offset:96
	s_waitcnt lgkmcnt(1)
	v_rcp_f32_e32 v74, v66
	v_rcp_f32_e32 v83, v67
	v_lshlrev_b64 v[66:67], 12, v[150:151]
	v_lshl_add_u64 v[66:67], s[2:3], 0, v[66:67]
	v_lshlrev_b32_e32 v202, 1, v154
	v_rcp_f32_e32 v84, v68
	v_rcp_f32_e32 v85, v69
	v_lshlrev_b32_e32 v68, 14, v155
	v_lshl_add_u64 v[66:67], v[66:67], 0, v[202:203]
	v_mov_b32_e32 v69, v203
	v_lshl_add_u64 v[66:67], v[66:67], 0, v[68:69]
	s_movk_i32 s3, 0x7fff
	s_waitcnt lgkmcnt(0)
	v_rcp_f32_e32 v70, v70
	v_rcp_f32_e32 v71, v71
	v_rcp_f32_e32 v72, v72
	v_rcp_f32_e32 v73, v73
	v_lshlrev_b32_e32 v68, 1, v154
	v_lshl_add_u32 v68, v155, 9, v68
	v_lshrrev_b32_e32 v69, 6, v0
	v_lshl_add_u32 v68, v69, 12, v68
	v_add_u32_e32 v68, 0x14000, v68
	v_mul_f32_e32 v2, v2, v75
	v_bfe_u32 v69, v2, 16, 1
	v_add3_u32 v2, v2, v69, s3
	ds_write_b16_d16_hi v68, v2
	v_mul_f32_e32 v50, v50, v75
	v_bfe_u32 v69, v50, 16, 1
	v_add3_u32 v50, v50, v69, s3
	ds_write_b16_d16_hi v68, v50 offset:64
	v_mul_f32_e32 v3, v3, v76
	v_bfe_u32 v69, v3, 16, 1
	v_add3_u32 v3, v3, v69, s3
	ds_write_b16_d16_hi v68, v3 offset:128
	v_mul_f32_e32 v51, v51, v76
	v_bfe_u32 v69, v51, 16, 1
	v_add3_u32 v51, v51, v69, s3
	ds_write_b16_d16_hi v68, v51 offset:192
	v_mul_f32_e32 v4, v4, v77
	v_bfe_u32 v69, v4, 16, 1
	v_add3_u32 v4, v4, v69, s3
	ds_write_b16_d16_hi v68, v4 offset:256
	v_mul_f32_e32 v52, v52, v77
	v_bfe_u32 v69, v52, 16, 1
	v_add3_u32 v52, v52, v69, s3
	ds_write_b16_d16_hi v68, v52 offset:320
	v_mul_f32_e32 v5, v5, v78
	v_bfe_u32 v69, v5, 16, 1
	v_add3_u32 v5, v5, v69, s3
	ds_write_b16_d16_hi v68, v5 offset:384
	v_mul_f32_e32 v53, v53, v78
	v_bfe_u32 v69, v53, 16, 1
	v_add3_u32 v53, v53, v69, s3
	ds_write_b16_d16_hi v68, v53 offset:448
	v_mul_f32_e32 v6, v6, v79
	v_bfe_u32 v69, v6, 16, 1
	v_add3_u32 v6, v6, v69, s3
	ds_write_b16_d16_hi v68, v6 offset:1024
	v_mul_f32_e32 v54, v54, v79
	v_bfe_u32 v69, v54, 16, 1
	v_add3_u32 v54, v54, v69, s3
	ds_write_b16_d16_hi v68, v54 offset:1088
	v_mul_f32_e32 v7, v7, v80
	v_bfe_u32 v69, v7, 16, 1
	v_add3_u32 v7, v7, v69, s3
	ds_write_b16_d16_hi v68, v7 offset:1152
	v_mul_f32_e32 v55, v55, v80
	v_bfe_u32 v69, v55, 16, 1
	v_add3_u32 v55, v55, v69, s3
	ds_write_b16_d16_hi v68, v55 offset:1216
	v_mul_f32_e32 v8, v8, v81
	v_bfe_u32 v69, v8, 16, 1
	v_add3_u32 v8, v8, v69, s3
	ds_write_b16_d16_hi v68, v8 offset:1280
	v_mul_f32_e32 v56, v56, v81
	v_bfe_u32 v69, v56, 16, 1
	v_add3_u32 v56, v56, v69, s3
	ds_write_b16_d16_hi v68, v56 offset:1344
	v_mul_f32_e32 v9, v9, v82
	v_bfe_u32 v69, v9, 16, 1
	v_add3_u32 v9, v9, v69, s3
	ds_write_b16_d16_hi v68, v9 offset:1408
	v_mul_f32_e32 v57, v57, v82
	v_bfe_u32 v69, v57, 16, 1
	v_add3_u32 v57, v57, v69, s3
	ds_write_b16_d16_hi v68, v57 offset:1472
	v_mul_f32_e32 v10, v10, v74
	v_bfe_u32 v69, v10, 16, 1
	v_add3_u32 v10, v10, v69, s3
	ds_write_b16_d16_hi v68, v10 offset:2048
	v_mul_f32_e32 v58, v58, v74
	v_bfe_u32 v69, v58, 16, 1
	v_add3_u32 v58, v58, v69, s3
	ds_write_b16_d16_hi v68, v58 offset:2112
	v_mul_f32_e32 v11, v11, v83
	v_bfe_u32 v69, v11, 16, 1
	v_add3_u32 v11, v11, v69, s3
	ds_write_b16_d16_hi v68, v11 offset:2176
	v_mul_f32_e32 v59, v59, v83
	v_bfe_u32 v69, v59, 16, 1
	v_add3_u32 v59, v59, v69, s3
	ds_write_b16_d16_hi v68, v59 offset:2240
	v_mul_f32_e32 v12, v12, v84
	v_bfe_u32 v69, v12, 16, 1
	v_add3_u32 v12, v12, v69, s3
	ds_write_b16_d16_hi v68, v12 offset:2304
	v_mul_f32_e32 v60, v60, v84
	v_bfe_u32 v69, v60, 16, 1
	v_add3_u32 v60, v60, v69, s3
	ds_write_b16_d16_hi v68, v60 offset:2368
	v_mul_f32_e32 v13, v13, v85
	v_bfe_u32 v69, v13, 16, 1
	v_add3_u32 v13, v13, v69, s3
	ds_write_b16_d16_hi v68, v13 offset:2432
	v_mul_f32_e32 v61, v61, v85
	v_bfe_u32 v69, v61, 16, 1
	v_add3_u32 v61, v61, v69, s3
	ds_write_b16_d16_hi v68, v61 offset:2496
	v_mul_f32_e32 v14, v14, v70
	v_bfe_u32 v69, v14, 16, 1
	v_add3_u32 v14, v14, v69, s3
	ds_write_b16_d16_hi v68, v14 offset:3072
	v_mul_f32_e32 v62, v62, v70
	v_bfe_u32 v69, v62, 16, 1
	v_add3_u32 v62, v62, v69, s3
	ds_write_b16_d16_hi v68, v62 offset:3136
	v_mul_f32_e32 v15, v15, v71
	v_bfe_u32 v69, v15, 16, 1
	v_add3_u32 v15, v15, v69, s3
	ds_write_b16_d16_hi v68, v15 offset:3200
	v_mul_f32_e32 v63, v63, v71
	v_bfe_u32 v69, v63, 16, 1
	v_add3_u32 v63, v63, v69, s3
	ds_write_b16_d16_hi v68, v63 offset:3264
	v_mul_f32_e32 v16, v16, v72
	v_bfe_u32 v69, v16, 16, 1
	v_add3_u32 v16, v16, v69, s3
	ds_write_b16_d16_hi v68, v16 offset:3328
	v_mul_f32_e32 v64, v64, v72
	v_bfe_u32 v69, v64, 16, 1
	v_add3_u32 v64, v64, v69, s3
	ds_write_b16_d16_hi v68, v64 offset:3392
	v_mul_f32_e32 v17, v17, v73
	v_bfe_u32 v69, v17, 16, 1
	v_add3_u32 v17, v17, v69, s3
	ds_write_b16_d16_hi v68, v17 offset:3456
	v_mul_f32_e32 v65, v65, v73
	v_bfe_u32 v69, v65, 16, 1
	v_add3_u32 v65, v65, v69, s3
	ds_write_b16_d16_hi v68, v65 offset:3520
	v_and_b32_e32 v3, 63, v0
	v_lshrrev_b32_e32 v52, 3, v3
	v_and_b32_e32 v3, 7, v3
	v_lshlrev_b32_e32 v2, 7, v52
	v_lshl_add_u32 v2, v3, 4, v2
	v_lshrrev_b32_e32 v53, 6, v0
	v_lshl_add_u32 v2, v53, 12, v2
	v_add_u32_e32 v2, 0x14000, v2
	v_lshlrev_b32_e32 v4, 12, v52
	v_lshl_add_u32 v4, v3, 4, v4
	v_lshlrev_b32_e32 v5, 14, v155
	v_sub_u32_e32 v4, v4, v5
	v_lshlrev_b32_e32 v5, 1, v154
	v_sub_u32_e32 v4, v4, v5
	v_ashrrev_i32_e32 v5, 31, v4
	v_add_co_u32_e32 v4, vcc, v66, v4
	v_addc_co_u32_e32 v5, vcc, v67, v5, vcc
	s_mov_b32 s2, 0x8000
	v_add_co_u32_e32 v6, vcc, s2, v4
	v_addc_co_u32_e32 v7, vcc, 0, v5, vcc
	v_add_co_u32_e32 v60, vcc, s2, v6
	v_addc_co_u32_e32 v61, vcc, 0, v7, vcc
	v_add_co_u32_e32 v62, vcc, s2, v60
	v_addc_co_u32_e32 v63, vcc, 0, v61, vcc
	s_waitcnt lgkmcnt(0)
	ds_read_b128 v[8:11], v2
	ds_read_b128 v[12:15], v2 offset:1024
	ds_read_b128 v[52:55], v2 offset:2048
	ds_read_b128 v[56:59], v2 offset:3072
	s_waitcnt lgkmcnt(3)
	global_store_dwordx4 v[4:5], v[8:11], off
	s_waitcnt lgkmcnt(2)
	global_store_dwordx4 v[6:7], v[12:15], off
	s_waitcnt lgkmcnt(1)
	global_store_dwordx4 v[60:61], v[52:55], off
	s_waitcnt lgkmcnt(0)
	global_store_dwordx4 v[62:63], v[56:59], off
	v_mul_f32_e32 v34, v34, v75
	v_bfe_u32 v69, v34, 16, 1
	v_add3_u32 v34, v34, v69, s3
	ds_write_b16_d16_hi v68, v34
	v_mul_f32_e32 v18, v18, v75
	v_bfe_u32 v69, v18, 16, 1
	v_add3_u32 v18, v18, v69, s3
	ds_write_b16_d16_hi v68, v18 offset:64
	v_mul_f32_e32 v35, v35, v76
	v_bfe_u32 v69, v35, 16, 1
	v_add3_u32 v35, v35, v69, s3
	ds_write_b16_d16_hi v68, v35 offset:128
	v_mul_f32_e32 v19, v19, v76
	v_bfe_u32 v69, v19, 16, 1
	v_add3_u32 v19, v19, v69, s3
	ds_write_b16_d16_hi v68, v19 offset:192
	v_mul_f32_e32 v36, v36, v77
	v_bfe_u32 v69, v36, 16, 1
	v_add3_u32 v36, v36, v69, s3
	ds_write_b16_d16_hi v68, v36 offset:256
	v_mul_f32_e32 v20, v20, v77
	v_bfe_u32 v69, v20, 16, 1
	v_add3_u32 v20, v20, v69, s3
	ds_write_b16_d16_hi v68, v20 offset:320
	v_mul_f32_e32 v37, v37, v78
	v_bfe_u32 v69, v37, 16, 1
	v_add3_u32 v37, v37, v69, s3
	ds_write_b16_d16_hi v68, v37 offset:384
	v_mul_f32_e32 v21, v21, v78
	v_bfe_u32 v69, v21, 16, 1
	v_add3_u32 v21, v21, v69, s3
	ds_write_b16_d16_hi v68, v21 offset:448
	v_mul_f32_e32 v38, v38, v79
	v_bfe_u32 v69, v38, 16, 1
	v_add3_u32 v38, v38, v69, s3
	ds_write_b16_d16_hi v68, v38 offset:1024
	v_mul_f32_e32 v22, v22, v79
	v_bfe_u32 v69, v22, 16, 1
	v_add3_u32 v22, v22, v69, s3
	ds_write_b16_d16_hi v68, v22 offset:1088
	v_mul_f32_e32 v39, v39, v80
	v_bfe_u32 v69, v39, 16, 1
	v_add3_u32 v39, v39, v69, s3
	ds_write_b16_d16_hi v68, v39 offset:1152
	v_mul_f32_e32 v23, v23, v80
	v_bfe_u32 v69, v23, 16, 1
	v_add3_u32 v23, v23, v69, s3
	ds_write_b16_d16_hi v68, v23 offset:1216
	v_mul_f32_e32 v40, v40, v81
	v_bfe_u32 v69, v40, 16, 1
	v_add3_u32 v40, v40, v69, s3
	ds_write_b16_d16_hi v68, v40 offset:1280
	v_mul_f32_e32 v24, v24, v81
	v_bfe_u32 v69, v24, 16, 1
	v_add3_u32 v24, v24, v69, s3
	ds_write_b16_d16_hi v68, v24 offset:1344
	v_mul_f32_e32 v41, v41, v82
	v_bfe_u32 v69, v41, 16, 1
	v_add3_u32 v41, v41, v69, s3
	ds_write_b16_d16_hi v68, v41 offset:1408
	v_mul_f32_e32 v25, v25, v82
	v_bfe_u32 v69, v25, 16, 1
	v_add3_u32 v25, v25, v69, s3
	ds_write_b16_d16_hi v68, v25 offset:1472
	v_mul_f32_e32 v42, v42, v74
	v_bfe_u32 v69, v42, 16, 1
	v_add3_u32 v42, v42, v69, s3
	ds_write_b16_d16_hi v68, v42 offset:2048
	v_mul_f32_e32 v26, v26, v74
	v_bfe_u32 v69, v26, 16, 1
	v_add3_u32 v26, v26, v69, s3
	ds_write_b16_d16_hi v68, v26 offset:2112
	v_mul_f32_e32 v43, v43, v83
	v_bfe_u32 v69, v43, 16, 1
	v_add3_u32 v43, v43, v69, s3
	ds_write_b16_d16_hi v68, v43 offset:2176
	v_mul_f32_e32 v27, v27, v83
	v_bfe_u32 v69, v27, 16, 1
	v_add3_u32 v27, v27, v69, s3
	ds_write_b16_d16_hi v68, v27 offset:2240
	v_mul_f32_e32 v44, v44, v84
	v_bfe_u32 v69, v44, 16, 1
	v_add3_u32 v44, v44, v69, s3
	ds_write_b16_d16_hi v68, v44 offset:2304
	v_mul_f32_e32 v28, v28, v84
	v_bfe_u32 v69, v28, 16, 1
	v_add3_u32 v28, v28, v69, s3
	ds_write_b16_d16_hi v68, v28 offset:2368
	v_mul_f32_e32 v45, v45, v85
	v_bfe_u32 v69, v45, 16, 1
	v_add3_u32 v45, v45, v69, s3
	ds_write_b16_d16_hi v68, v45 offset:2432
	v_mul_f32_e32 v29, v29, v85
	v_bfe_u32 v69, v29, 16, 1
	v_add3_u32 v29, v29, v69, s3
	ds_write_b16_d16_hi v68, v29 offset:2496
	v_mul_f32_e32 v46, v46, v70
	v_bfe_u32 v69, v46, 16, 1
	v_add3_u32 v46, v46, v69, s3
	ds_write_b16_d16_hi v68, v46 offset:3072
	v_mul_f32_e32 v30, v30, v70
	v_bfe_u32 v69, v30, 16, 1
	v_add3_u32 v30, v30, v69, s3
	ds_write_b16_d16_hi v68, v30 offset:3136
	v_mul_f32_e32 v47, v47, v71
	v_bfe_u32 v69, v47, 16, 1
	v_add3_u32 v47, v47, v69, s3
	ds_write_b16_d16_hi v68, v47 offset:3200
	v_mul_f32_e32 v31, v31, v71
	v_bfe_u32 v69, v31, 16, 1
	v_add3_u32 v31, v31, v69, s3
	ds_write_b16_d16_hi v68, v31 offset:3264
	v_mul_f32_e32 v48, v48, v72
	v_bfe_u32 v69, v48, 16, 1
	v_add3_u32 v48, v48, v69, s3
	ds_write_b16_d16_hi v68, v48 offset:3328
	v_mul_f32_e32 v32, v32, v72
	v_bfe_u32 v69, v32, 16, 1
	v_add3_u32 v32, v32, v69, s3
	ds_write_b16_d16_hi v68, v32 offset:3392
	v_mul_f32_e32 v49, v49, v73
	v_bfe_u32 v69, v49, 16, 1
	v_add3_u32 v49, v49, v69, s3
	ds_write_b16_d16_hi v68, v49 offset:3456
	v_mul_f32_e32 v33, v33, v73
	v_bfe_u32 v69, v33, 16, 1
	v_add3_u32 v33, v33, v69, s3
	ds_write_b16_d16_hi v68, v33 offset:3520
	s_waitcnt lgkmcnt(0)
	ds_read_b128 v[8:11], v2
	ds_read_b128 v[12:15], v2 offset:1024
	ds_read_b128 v[52:55], v2 offset:2048
	ds_read_b128 v[56:59], v2 offset:3072
	s_waitcnt lgkmcnt(3)
	global_store_dwordx4 v[4:5], v[8:11], off offset:128
	s_waitcnt lgkmcnt(2)
	global_store_dwordx4 v[6:7], v[12:15], off offset:128
	s_waitcnt lgkmcnt(1)
	global_store_dwordx4 v[60:61], v[52:55], off offset:128
	s_waitcnt lgkmcnt(0)
	global_store_dwordx4 v[62:63], v[56:59], off offset:128
	s_waitcnt vmcnt(63) expcnt(7) lgkmcnt(15)
	s_barrier
	s_mov_b64 s[2:3], -1
